# attention row-max exchange across lane halves: ds_bpermute+lgkmcnt(0) replaced by v_permlane32_swap (exact max, no LDS round trip)
# speedup vs baseline: 1.0045x; 1.0045x over previous
; #define MFMA32(a, b, c) __builtin_amdgcn_mfma_f32_32x32x16_bf16((a), (b), (c), 0, 0, 0)
; template <int DQK, bool WIN>
; DI void attn_item(const u16* __restrict__ Qb, int ldq, const u16* __restrict__ Kb, int ldk, const u16* __restrict__ Vtb, int qb,
;                   float qscale, float sink2, const u16* __restrict__ zb, int ldz, u16* __restrict__ ob, int ldo, u16* lds) {
;     ...
;     bool active = (k0 <= q0 + 31);
;     if (WIN) active = active && (k0 + 63 >= q0 - 127);
;     if (active) {
;       f32x16 st[2];
; #pragma unroll
;       for (int kb = 0; kb < 2; ++kb) {
; #pragma unroll
;         for (int i = 0; i < 16; ++i) st[kb][i] = 0.f;
; #pragma unroll
;         for (int s = 0; s < NKS; ++s) {
;           bf16x8 a = *(const bf16x8*)(ks + (kb * 32 + r) * KST + 16 * s + 8 * hh);
;           st[kb] = MFMA32(a, qf[s], st[kb]);
;         }
;       }
.LBB0_233:
	s_add_i32 s0, s31, -1
	s_add_i32 s1, s20, 0xffffff40
	s_cmp_lt_u32 s0, s29
	v_cmp_le_i32_e64 s[8:9], s1, v154
	s_mov_b64 s[24:25], -1
	s_cbranch_scc1 .LBB0_239
	v_mov_b64_e32 v[64:65], v[16:17]
	v_mov_b64_e32 v[48:49], v[32:33]
	v_mov_b32_e32 v158, v157
	v_mov_b32_e32 v0, v142
	v_mov_b64_e32 v[62:63], v[14:15]
	v_mov_b64_e32 v[60:61], v[12:13]
	v_mov_b64_e32 v[58:59], v[10:11]
	v_mov_b64_e32 v[56:57], v[8:9]
	v_mov_b64_e32 v[54:55], v[6:7]
	v_mov_b64_e32 v[52:53], v[4:5]
	v_mov_b64_e32 v[50:51], v[2:3]
	v_mov_b64_e32 v[46:47], v[30:31]
	v_mov_b64_e32 v[44:45], v[28:29]
	v_mov_b64_e32 v[42:43], v[26:27]
	v_mov_b64_e32 v[40:41], v[24:25]
	v_mov_b64_e32 v[38:39], v[22:23]
	v_mov_b64_e32 v[36:37], v[20:21]
	v_mov_b64_e32 v[34:35], v[18:19]
	s_and_saveexec_b64 s[24:25], s[8:9]
	s_cbranch_execz .LBB0_238
	ds_read_b128 v[206:209], v155
	ds_read_b128 v[210:213], v155 offset:32
	ds_read_b128 v[214:217], v155 offset:64
	ds_read_b128 v[218:221], v155 offset:6688
	ds_read_b128 v[222:225], v155 offset:96
	ds_read_b128 v[226:229], v155 offset:128
	ds_read_b128 v[230:233], v155 offset:160
	ds_read_b128 v[234:237], v155 offset:6656
	ds_read_b128 v[238:241], v155 offset:6720
	ds_read_b128 v[242:245], v155 offset:6752
	ds_read_b128 v[246:249], v155 offset:6784
	ds_read_b128 v[250:253], v155 offset:6816
	v_mov_b32_e32 v196, v142
	s_waitcnt lgkmcnt(11)
	v_mfma_f32_32x32x16_bf16 v[50:65], v[206:209], v[66:69], 0
	s_waitcnt lgkmcnt(10)
	v_mfma_f32_32x32x16_bf16 v[50:65], v[210:213], v[70:73], v[50:65]
	s_waitcnt lgkmcnt(9)
	v_mfma_f32_32x32x16_bf16 v[50:65], v[214:217], v[74:77], v[50:65]
	s_waitcnt lgkmcnt(7)
	v_mfma_f32_32x32x16_bf16 v[50:65], v[222:225], v[78:81], v[50:65]
	s_waitcnt lgkmcnt(6)
	v_mfma_f32_32x32x16_bf16 v[50:65], v[226:229], v[82:85], v[50:65]
	s_waitcnt lgkmcnt(5)
	v_mfma_f32_32x32x16_bf16 v[50:65], v[230:233], v[86:89], v[50:65]
	s_waitcnt lgkmcnt(4)
	v_mfma_f32_32x32x16_bf16 v[34:49], v[234:237], v[66:69], 0
	v_mfma_f32_32x32x16_bf16 v[34:49], v[218:221], v[70:73], v[34:49]
	s_waitcnt lgkmcnt(3)
	v_mfma_f32_32x32x16_bf16 v[34:49], v[238:241], v[74:77], v[34:49]
	s_waitcnt lgkmcnt(2)
	v_mfma_f32_32x32x16_bf16 v[34:49], v[242:245], v[78:81], v[34:49]
	s_waitcnt lgkmcnt(1)
	v_mfma_f32_32x32x16_bf16 v[34:49], v[246:249], v[82:85], v[34:49]
	s_waitcnt lgkmcnt(0)
; template <int DQK, bool WIN>
; DI void attn_item(const u16* __restrict__ Qb, int ldq, const u16* __restrict__ Kb, int ldk, const u16* __restrict__ Vtb, int qb,
;                   float qscale, float sink2, const u16* __restrict__ zb, int ldz, u16* __restrict__ ob, int ldo, u16* lds) {
;     ...
;       float mx = -INFINITY;
; #pragma unroll
;       for (int kb = 0; kb < 2; ++kb)
; #pragma unroll
;         for (int i = 0; i < 16; ++i) {
;           float v = st[kb][i];
;           if (MASK) {
;             int kg = k0 + kb * 32 + (i & 3) + 8 * (i >> 2) + 4 * hh;
;             bool ok = kg <= qrow;
;             if (WIN) ok = ok && (qrow - kg < 128);
;             v = ok ? v : -INFINITY;
;             st[kb][i] = v;
;           }
;           mx = fmaxf(mx, v);
;         }
;       mx = fmaxf(mx, __shfl_xor(mx, 32));
;       const float mn = fmaxf(m, mx);
;       if (__any(mn != m)) {
;         const float alpha = __builtin_amdgcn_exp2f((m - mn) * qscale);
;         lsum *= alpha;
; #pragma unroll
;         for (int i = 0; i < 16; ++i) { o[0][i] *= alpha; o[1][i] *= alpha; }
;       }
	v_mfma_f32_32x32x16_bf16 v[34:49], v[250:253], v[86:89], v[34:49]
	v_add_u32_e32 v158, s20, v146
	v_add_u32_e32 v0, 0xffffff40, v158
	v_cmp_le_i32_e32 vcc, v0, v130
	s_nop 1
	v_cndmask_b32_e32 v159, v176, v50, vcc
	v_cmp_lt_i32_e32 vcc, v0, v130
	s_nop 1
	v_cndmask_b32_e32 v0, v176, v51, vcc
	v_add_u32_e32 v51, 0xffffff42, v158
	v_cmp_le_i32_e32 vcc, v51, v130
	v_add_u32_e32 v51, 0xffffff43, v158
	v_max3_f32 v50, v159, s94, v0
	v_cndmask_b32_e32 v161, v176, v52, vcc
	v_cmp_le_i32_e32 vcc, v51, v130
	v_add_u32_e32 v51, 0xffffff48, v158
	s_nop 0
	v_cndmask_b32_e32 v160, v176, v53, vcc
	v_cmp_le_i32_e32 vcc, v51, v130
	v_add_u32_e32 v51, 0xffffff49, v158
	v_max3_f32 v50, v50, v161, v160
	v_cndmask_b32_e32 v164, v176, v54, vcc
	v_cmp_le_i32_e32 vcc, v51, v130
	v_add_u32_e32 v51, 0xffffff4a, v158
	s_nop 0
	v_cndmask_b32_e32 v162, v176, v55, vcc
	v_cmp_le_i32_e32 vcc, v51, v130
	v_add_u32_e32 v51, 0xffffff4b, v158
	v_max3_f32 v50, v50, v164, v162
	v_cndmask_b32_e32 v165, v176, v56, vcc
	v_cmp_le_i32_e32 vcc, v51, v130
	v_add_u32_e32 v51, 0xffffff50, v158
	s_nop 0
	v_cndmask_b32_e32 v166, v176, v57, vcc
	v_cmp_le_i32_e32 vcc, v51, v130
	v_add_u32_e32 v51, 0xffffff51, v158
	v_max3_f32 v50, v50, v165, v166
	v_cndmask_b32_e32 v205, v176, v58, vcc
	v_cmp_le_i32_e32 vcc, v51, v130
	v_add_u32_e32 v51, 0xffffff52, v158
	s_nop 0
	v_cndmask_b32_e32 v203, v176, v59, vcc
	v_cmp_le_i32_e32 vcc, v51, v130
	v_add_u32_e32 v51, 0xffffff53, v158
	v_max3_f32 v50, v50, v205, v203
	v_cndmask_b32_e32 v204, v176, v60, vcc
	v_cmp_le_i32_e32 vcc, v51, v130
	v_add_u32_e32 v51, 0xffffff58, v158
	s_nop 0
	v_cndmask_b32_e32 v201, v176, v61, vcc
	v_cmp_le_i32_e32 vcc, v51, v130
	v_add_u32_e32 v51, 0xffffff59, v158
	v_max3_f32 v50, v50, v204, v201
	v_cndmask_b32_e32 v202, v176, v62, vcc
	v_cmp_le_i32_e32 vcc, v51, v130
	v_add_u32_e32 v51, 0xffffff5a, v158
	s_nop 0
	v_cndmask_b32_e32 v199, v176, v63, vcc
	v_cmp_le_i32_e32 vcc, v51, v130
	v_add_u32_e32 v51, 0xffffff5b, v158
	v_max3_f32 v50, v50, v202, v199
	v_cndmask_b32_e32 v200, v176, v64, vcc
	v_cmp_le_i32_e32 vcc, v51, v130
	v_add_u32_e32 v51, 0xffffff60, v158
	s_nop 0
	v_cndmask_b32_e32 v197, v176, v65, vcc
	v_cmp_le_i32_e32 vcc, v51, v130
	v_max3_f32 v50, v50, v200, v197
	s_nop 0
	v_cndmask_b32_e32 v198, v176, v34, vcc
	v_add_u32_e32 v34, 0xffffff61, v158
	v_cmp_le_i32_e32 vcc, v34, v130
	s_nop 1
	v_cndmask_b32_e32 v195, v176, v35, vcc
	v_add_u32_e32 v35, 0xffffff62, v158
	v_cmp_le_i32_e32 vcc, v35, v130
	v_add_u32_e32 v35, 0xffffff63, v158
	v_max3_f32 v34, v50, v198, v195
	v_cndmask_b32_e32 v194, v176, v36, vcc
	v_cmp_le_i32_e32 vcc, v35, v130
	v_add_u32_e32 v35, 0xffffff68, v158
	v_and_b32_e32 v36, 64, v172
	v_cndmask_b32_e32 v193, v176, v37, vcc
	v_cmp_le_i32_e32 vcc, v35, v130
	v_add_u32_e32 v35, 0xffffff69, v158
	v_max3_f32 v34, v34, v194, v193
	v_cndmask_b32_e32 v192, v176, v38, vcc
	v_cmp_le_i32_e32 vcc, v35, v130
	v_add_u32_e32 v35, 0xffffff6a, v158
	v_add_u32_e32 v36, 64, v36
	v_cndmask_b32_e32 v167, v176, v39, vcc
	v_cmp_le_i32_e32 vcc, v35, v130
	v_add_u32_e32 v35, 0xffffff6b, v158
	v_max3_f32 v34, v34, v192, v167
	v_cndmask_b32_e32 v182, v176, v40, vcc
	v_cmp_le_i32_e32 vcc, v35, v130
	v_add_u32_e32 v35, 0xffffff70, v158
	v_mov_b64_e32 v[64:65], v[16:17]
	v_cndmask_b32_e32 v183, v176, v41, vcc
	v_cmp_le_i32_e32 vcc, v35, v130
	v_add_u32_e32 v35, 0xffffff71, v158
	v_max3_f32 v34, v34, v182, v183
	v_cndmask_b32_e32 v184, v176, v42, vcc
	v_cmp_le_i32_e32 vcc, v35, v130
	v_add_u32_e32 v35, 0xffffff72, v158
	v_mov_b64_e32 v[62:63], v[14:15]
	v_cndmask_b32_e32 v185, v176, v43, vcc
	v_cmp_le_i32_e32 vcc, v35, v130
	v_add_u32_e32 v35, 0xffffff73, v158
	v_max3_f32 v34, v34, v184, v185
	v_cndmask_b32_e32 v186, v176, v44, vcc
	v_cmp_le_i32_e32 vcc, v35, v130
	v_add_u32_e32 v35, 0xffffff78, v158
	v_mov_b64_e32 v[60:61], v[12:13]
	v_cndmask_b32_e32 v187, v176, v45, vcc
	v_cmp_le_i32_e32 vcc, v35, v130
	v_add_u32_e32 v35, 0xffffff79, v158
	v_max3_f32 v34, v34, v186, v187
	v_cndmask_b32_e32 v188, v176, v46, vcc
	v_cmp_le_i32_e32 vcc, v35, v130
	v_add_u32_e32 v35, 0xffffff7a, v158
	v_mov_b64_e32 v[58:59], v[10:11]
	v_cndmask_b32_e32 v189, v176, v47, vcc
	v_cmp_le_i32_e32 vcc, v35, v130
	v_add_u32_e32 v35, 0xffffff7b, v158
	v_max3_f32 v34, v34, v188, v189
	v_cndmask_b32_e32 v190, v176, v48, vcc
	v_cmp_le_i32_e32 vcc, v35, v130
	v_xor_b32_e32 v35, 32, v172
	v_mov_b64_e32 v[56:57], v[8:9]
	v_cndmask_b32_e32 v191, v176, v49, vcc
	v_cmp_lt_i32_e32 vcc, v35, v36
	v_max3_f32 v34, v34, v190, v191
	v_mov_b64_e32 v[54:55], v[6:7]
	v_cndmask_b32_e32 v35, v172, v35, vcc
	v_lshlrev_b32_e32 v35, 2, v35
	v_mov_b32_e32 v35, v34
	s_nop 1
	v_permlane32_swap_b32 v35, v34
	v_mov_b64_e32 v[52:53], v[4:5]
	v_mov_b64_e32 v[50:51], v[2:3]
	s_waitcnt lgkmcnt(0)
	v_max3_f32 v158, v157, v34, v35
	v_mov_b64_e32 v[48:49], v[32:33]
	v_cmp_neq_f32_e32 vcc, v158, v157
	v_mov_b64_e32 v[46:47], v[30:31]
	v_mov_b64_e32 v[44:45], v[28:29]
	v_mov_b64_e32 v[42:43], v[26:27]
	v_mov_b64_e32 v[40:41], v[24:25]
	v_mov_b64_e32 v[38:39], v[22:23]
	v_mov_b64_e32 v[36:37], v[20:21]
	v_mov_b64_e32 v[34:35], v[18:19]
	s_cbranch_vccz .LBB0_237
	v_sub_f32_e32 v34, v157, v158
	v_mul_f32_e32 v34, 0x3e16c740, v34
	v_exp_f32_e32 v50, v34
	s_nop 0
	v_mul_f32_e32 v196, v142, v50
	v_pk_mul_f32 v[48:49], v[32:33], v[50:51] op_sel_hi:[1,0]
	v_pk_mul_f32 v[46:47], v[30:31], v[50:51] op_sel_hi:[1,0]
	v_pk_mul_f32 v[44:45], v[28:29], v[50:51] op_sel_hi:[1,0]
	v_pk_mul_f32 v[42:43], v[26:27], v[50:51] op_sel_hi:[1,0]
	v_pk_mul_f32 v[40:41], v[24:25], v[50:51] op_sel_hi:[1,0]
	v_pk_mul_f32 v[38:39], v[22:23], v[50:51] op_sel_hi:[1,0]
	v_pk_mul_f32 v[36:37], v[20:21], v[50:51] op_sel_hi:[1,0]
	v_pk_mul_f32 v[34:35], v[18:19], v[50:51] op_sel_hi:[1,0]
	v_pk_mul_f32 v[64:65], v[16:17], v[50:51] op_sel_hi:[1,0]
	v_pk_mul_f32 v[62:63], v[14:15], v[50:51] op_sel_hi:[1,0]
	v_pk_mul_f32 v[60:61], v[12:13], v[50:51] op_sel_hi:[1,0]
	v_pk_mul_f32 v[58:59], v[10:11], v[50:51] op_sel_hi:[1,0]
	v_pk_mul_f32 v[56:57], v[8:9], v[50:51] op_sel_hi:[1,0]
	v_pk_mul_f32 v[54:55], v[6:7], v[50:51] op_sel_hi:[1,0]
	v_pk_mul_f32 v[52:53], v[4:5], v[50:51] op_sel_hi:[1,0]
	v_pk_mul_f32 v[50:51], v[2:3], v[50:51] op_sel_hi:[1,0]

; #define MFMA32(a, b, c) __builtin_amdgcn_mfma_f32_32x32x16_bf16((a), (b), (c), 0, 0, 0)
; template <int DQK, bool WIN>
; DI void attn_item(const u16* __restrict__ Qb, int ldq, const u16* __restrict__ Kb, int ldk, const u16* __restrict__ Vtb, int qb,
;                   float qscale, float sink2, const u16* __restrict__ zb, int ldz, u16* __restrict__ ob, int ldo, u16* lds) {
;     ...
;       f32x16 st[2];
; #pragma unroll
;       for (int kb = 0; kb < 2; ++kb) {
; #pragma unroll
;         for (int i = 0; i < 16; ++i) st[kb][i] = 0.f;
; #pragma unroll
;         for (int s = 0; s < NKS; ++s) {
;           bf16x8 a = *(const bf16x8*)(ks + (kb * 32 + r) * KST + 16 * s + 8 * hh);
;           st[kb] = MFMA32(a, qf[s], st[kb]);
;         }
;       }
;       float mx = -INFINITY;
; #pragma unroll
;       for (int kb = 0; kb < 2; ++kb)
; #pragma unroll
;         for (int i = 0; i < 16; ++i) {
;           float v = st[kb][i];
;           if (MASK) {
;             int kg = k0 + kb * 32 + (i & 3) + 8 * (i >> 2) + 4 * hh;
;             bool ok = kg <= qrow;
;             if (WIN) ok = ok && (qrow - kg < 128);
;             v = ok ? v : -INFINITY;
;             st[kb][i] = v;
;           }
;           mx = fmaxf(mx, v);
;         }
;       mx = fmaxf(mx, __shfl_xor(mx, 32));
;       const float mn = fmaxf(m, mx);
;       if (__any(mn != m)) {
;         const float alpha = __builtin_amdgcn_exp2f((m - mn) * qscale);
;         lsum *= alpha;
; #pragma unroll
;         for (int i = 0; i < 16; ++i) { o[0][i] *= alpha; o[1][i] *= alpha; }
;       }
.LBB0_239:
	s_andn2_b64 vcc, exec, s[24:25]
	s_cbranch_vccnz .LBB0_245
	s_and_saveexec_b64 s[24:25], s[8:9]
	s_cbranch_execz .LBB0_244
	ds_read_b128 v[164:167], v155
	ds_read_b128 v[182:185], v155 offset:32
	ds_read_b128 v[186:189], v155 offset:64
	ds_read_b128 v[190:193], v155 offset:6688
	ds_read_b128 v[194:197], v155 offset:96
	ds_read_b128 v[198:201], v155 offset:128
	ds_read_b128 v[202:205], v155 offset:160
	ds_read_b128 v[206:209], v155 offset:6656
	ds_read_b128 v[210:213], v155 offset:6720
	ds_read_b128 v[214:217], v155 offset:6752
	ds_read_b128 v[218:221], v155 offset:6784
	ds_read_b128 v[222:225], v155 offset:6816
	s_waitcnt lgkmcnt(11)
	v_mfma_f32_32x32x16_bf16 v[50:65], v[164:167], v[66:69], 0
	s_waitcnt lgkmcnt(10)
	v_mfma_f32_32x32x16_bf16 v[50:65], v[182:185], v[70:73], v[50:65]
	s_waitcnt lgkmcnt(9)
	v_mfma_f32_32x32x16_bf16 v[50:65], v[186:189], v[74:77], v[50:65]
	s_waitcnt lgkmcnt(7)
	v_mfma_f32_32x32x16_bf16 v[50:65], v[194:197], v[78:81], v[50:65]
	s_waitcnt lgkmcnt(6)
	v_mfma_f32_32x32x16_bf16 v[50:65], v[198:201], v[82:85], v[50:65]
	s_waitcnt lgkmcnt(5)
	v_mfma_f32_32x32x16_bf16 v[50:65], v[202:205], v[86:89], v[50:65]
	s_waitcnt lgkmcnt(4)
	v_mfma_f32_32x32x16_bf16 v[34:49], v[206:209], v[66:69], 0
	s_nop 8
	s_nop 0
	v_max3_f32 v0, v50, s94, v51
	v_max3_f32 v0, v0, v52, v53
	v_max3_f32 v0, v0, v54, v55
	v_max3_f32 v0, v0, v56, v57
	v_max3_f32 v0, v0, v58, v59
	v_max3_f32 v0, v0, v60, v61
	v_max3_f32 v0, v0, v62, v63
	v_mfma_f32_32x32x16_bf16 v[34:49], v[190:193], v[70:73], v[34:49]
	v_max3_f32 v0, v0, v64, v65
	s_waitcnt lgkmcnt(3)
	v_mfma_f32_32x32x16_bf16 v[34:49], v[210:213], v[74:77], v[34:49]
	s_waitcnt lgkmcnt(2)
	v_mfma_f32_32x32x16_bf16 v[34:49], v[214:217], v[78:81], v[34:49]
	s_waitcnt lgkmcnt(1)
	v_mfma_f32_32x32x16_bf16 v[34:49], v[218:221], v[82:85], v[34:49]
	s_waitcnt lgkmcnt(0)
	v_mfma_f32_32x32x16_bf16 v[34:49], v[222:225], v[86:89], v[34:49]
	v_and_b32_e32 v159, 64, v172
	v_xor_b32_e32 v158, 32, v172
	v_add_u32_e32 v159, 64, v159
	v_cmp_lt_i32_e32 vcc, v158, v159
	s_nop 7
	v_max3_f32 v0, v0, v34, v35
	v_max3_f32 v0, v0, v36, v37
	v_max3_f32 v0, v0, v38, v39
	v_max3_f32 v0, v0, v40, v41
	v_max3_f32 v0, v0, v42, v43
	v_max3_f32 v0, v0, v44, v45
	v_max3_f32 v0, v0, v46, v47
	v_cndmask_b32_e32 v158, v172, v158, vcc
	v_max3_f32 v0, v0, v48, v49
	v_lshlrev_b32_e32 v158, 2, v158
	v_mov_b32_e32 v158, v0
	s_nop 1
	v_permlane32_swap_b32 v158, v0
	s_waitcnt lgkmcnt(0)
	v_max3_f32 v0, v157, v0, v158
	v_cmp_neq_f32_e32 vcc, v0, v157
	s_cbranch_vccz .LBB0_243
	v_sub_f32_e32 v157, v157, v0
	v_mul_f32_e32 v157, 0x3e16c740, v157
	v_exp_f32_e32 v158, v157
	s_nop 0
	v_mul_f32_e32 v142, v142, v158
	v_pk_mul_f32 v[32:33], v[32:33], v[158:159] op_sel_hi:[1,0]
	v_pk_mul_f32 v[30:31], v[30:31], v[158:159] op_sel_hi:[1,0]
	v_pk_mul_f32 v[28:29], v[28:29], v[158:159] op_sel_hi:[1,0]
	v_pk_mul_f32 v[26:27], v[26:27], v[158:159] op_sel_hi:[1,0]
	v_pk_mul_f32 v[24:25], v[24:25], v[158:159] op_sel_hi:[1,0]
	v_pk_mul_f32 v[22:23], v[22:23], v[158:159] op_sel_hi:[1,0]
	v_pk_mul_f32 v[20:21], v[20:21], v[158:159] op_sel_hi:[1,0]
	v_pk_mul_f32 v[18:19], v[18:19], v[158:159] op_sel_hi:[1,0]
	v_pk_mul_f32 v[16:17], v[16:17], v[158:159] op_sel_hi:[1,0]
	v_pk_mul_f32 v[14:15], v[14:15], v[158:159] op_sel_hi:[1,0]
	v_pk_mul_f32 v[12:13], v[12:13], v[158:159] op_sel_hi:[1,0]
	v_pk_mul_f32 v[10:11], v[10:11], v[158:159] op_sel_hi:[1,0]
	v_pk_mul_f32 v[8:9], v[8:9], v[158:159] op_sel_hi:[1,0]
	v_pk_mul_f32 v[6:7], v[6:7], v[158:159] op_sel_hi:[1,0]
	v_pk_mul_f32 v[4:5], v[4:5], v[158:159] op_sel_hi:[1,0]
	v_pk_mul_f32 v[2:3], v[2:3], v[158:159] op_sel_hi:[1,0]

; #define MFMA32(a, b, c) __builtin_amdgcn_mfma_f32_32x32x16_bf16((a), (b), (c), 0, 0, 0)
; template <int DQK, bool WIN>
; DI void attn_item(const u16* __restrict__ Qb, int ldq, const u16* __restrict__ Kb, int ldk, const u16* __restrict__ Vtb, int qb,
;                   float qscale, float sink2, const u16* __restrict__ zb, int ldz, u16* __restrict__ ob, int ldo, u16* lds) {
;     ...
;       f32x16 st[2];
; #pragma unroll
;       for (int kb = 0; kb < 2; ++kb) {
; #pragma unroll
;         for (int i = 0; i < 16; ++i) st[kb][i] = 0.f;
; #pragma unroll
;         for (int s = 0; s < NKS; ++s) {
;           bf16x8 a = *(const bf16x8*)(ks + (kb * 32 + r) * KST + 16 * s + 8 * hh);
;           st[kb] = MFMA32(a, qf[s], st[kb]);
;         }
;       }
;     ...
;     if (WIN || kt >= 2 * qb) tile_body(kt, 0, std::true_type{}); else tile_body(kt, 0, std::false_type{});
;     swrite(rkB, rvB, 1);
;     __syncthreads();
;     if (kt + 3 <= kt_hi) gload(rkB, rvB, kt + 3);
;     if (WIN || kt + 1 >= 2 * qb) tile_body(kt + 1, 1, std::true_type{}); else tile_body(kt + 1, 1, std::false_type{});
.LBB0_247:
	s_add_i32 s0, s20, 0xffffff80
	s_cmp_lt_u32 s31, s29
	v_cmp_le_i32_e64 s[8:9], s0, v154
	s_mov_b64 s[24:25], -1
	s_cbranch_scc1 .LBB0_257
	v_mov_b64_e32 v[2:3], v[50:51]
	v_mov_b64_e32 v[18:19], v[34:35]
	v_mov_b32_e32 v157, v158
	v_mov_b32_e32 v142, v0
	v_mov_b64_e32 v[4:5], v[52:53]
	v_mov_b64_e32 v[6:7], v[54:55]
	v_mov_b64_e32 v[8:9], v[56:57]
	v_mov_b64_e32 v[10:11], v[58:59]
	v_mov_b64_e32 v[12:13], v[60:61]
	v_mov_b64_e32 v[14:15], v[62:63]
	v_mov_b64_e32 v[16:17], v[64:65]
	v_mov_b64_e32 v[20:21], v[36:37]
	v_mov_b64_e32 v[22:23], v[38:39]
	v_mov_b64_e32 v[24:25], v[40:41]
	v_mov_b64_e32 v[26:27], v[42:43]
	v_mov_b64_e32 v[28:29], v[44:45]
	v_mov_b64_e32 v[30:31], v[46:47]
	v_mov_b64_e32 v[32:33], v[48:49]
	s_and_saveexec_b64 s[24:25], s[8:9]
	s_cbranch_execz .LBB0_252
	ds_read_b128 v[206:209], v155 offset:22528
	ds_read_b128 v[210:213], v155 offset:22560
	ds_read_b128 v[214:217], v155 offset:22592
	ds_read_b128 v[218:221], v155 offset:29216
	ds_read_b128 v[222:225], v155 offset:22624
	ds_read_b128 v[226:229], v155 offset:22656
	ds_read_b128 v[230:233], v155 offset:22688
	ds_read_b128 v[234:237], v155 offset:29184
	ds_read_b128 v[238:241], v155 offset:29248
	ds_read_b128 v[242:245], v155 offset:29280
	ds_read_b128 v[246:249], v155 offset:29312
	ds_read_b128 v[250:253], v155 offset:29344
	v_add_u32_e32 v142, s20, v146
	v_add_u32_e32 v157, 0xffffff80, v142
	v_cmp_le_i32_e32 vcc, v157, v130
	s_waitcnt lgkmcnt(11)
	v_mfma_f32_32x32x16_bf16 v[18:33], v[206:209], v[66:69], 0
	s_waitcnt lgkmcnt(10)
	v_mfma_f32_32x32x16_bf16 v[18:33], v[210:213], v[70:73], v[18:33]
	s_waitcnt lgkmcnt(9)
	v_mfma_f32_32x32x16_bf16 v[18:33], v[214:217], v[74:77], v[18:33]
	s_waitcnt lgkmcnt(7)
	v_mfma_f32_32x32x16_bf16 v[18:33], v[222:225], v[78:81], v[18:33]
	s_waitcnt lgkmcnt(6)
	v_mfma_f32_32x32x16_bf16 v[18:33], v[226:229], v[82:85], v[18:33]
	s_waitcnt lgkmcnt(5)
	v_mfma_f32_32x32x16_bf16 v[18:33], v[230:233], v[86:89], v[18:33]
	s_waitcnt lgkmcnt(4)
	v_mfma_f32_32x32x16_bf16 v[2:17], v[234:237], v[66:69], 0
	v_mfma_f32_32x32x16_bf16 v[2:17], v[218:221], v[70:73], v[2:17]
	s_waitcnt lgkmcnt(3)
	v_mfma_f32_32x32x16_bf16 v[2:17], v[238:241], v[74:77], v[2:17]
	s_waitcnt lgkmcnt(2)
	v_mfma_f32_32x32x16_bf16 v[2:17], v[242:245], v[78:81], v[2:17]
	s_waitcnt lgkmcnt(1)
	v_mfma_f32_32x32x16_bf16 v[2:17], v[246:249], v[82:85], v[2:17]
	s_waitcnt lgkmcnt(0)
; template <int DQK, bool WIN>
; DI void attn_item(const u16* __restrict__ Qb, int ldq, const u16* __restrict__ Kb, int ldk, const u16* __restrict__ Vtb, int qb,
;                   float qscale, float sink2, const u16* __restrict__ zb, int ldz, u16* __restrict__ ob, int ldo, u16* lds) {
;     ...
;       float mx = -INFINITY;
; #pragma unroll
;       for (int kb = 0; kb < 2; ++kb)
; #pragma unroll
;         for (int i = 0; i < 16; ++i) {
;           float v = st[kb][i];
;           if (MASK) {
;             int kg = k0 + kb * 32 + (i & 3) + 8 * (i >> 2) + 4 * hh;
;             bool ok = kg <= qrow;
;             if (WIN) ok = ok && (qrow - kg < 128);
;             v = ok ? v : -INFINITY;
;             st[kb][i] = v;
;           }
;           mx = fmaxf(mx, v);
;         }
;       mx = fmaxf(mx, __shfl_xor(mx, 32));
;       const float mn = fmaxf(m, mx);
;       if (__any(mn != m)) {
;         const float alpha = __builtin_amdgcn_exp2f((m - mn) * qscale);
;         lsum *= alpha;
; #pragma unroll
;         for (int i = 0; i < 16; ++i) { o[0][i] *= alpha; o[1][i] *= alpha; }
;       }
	v_mfma_f32_32x32x16_bf16 v[2:17], v[250:253], v[86:89], v[2:17]
	s_nop 0
	v_cndmask_b32_e32 v167, v176, v18, vcc
	v_cmp_lt_i32_e32 vcc, v157, v130
	s_nop 1
	v_cndmask_b32_e32 v166, v176, v19, vcc
	v_add_u32_e32 v19, 0xffffff82, v142
	v_cmp_le_i32_e32 vcc, v19, v130
	v_add_u32_e32 v19, 0xffffff83, v142
	v_max3_f32 v18, v167, s94, v166
	v_cndmask_b32_e32 v182, v176, v20, vcc
	v_cmp_le_i32_e32 vcc, v19, v130
	v_add_u32_e32 v19, 0xffffff88, v142
	s_nop 0
	v_cndmask_b32_e32 v183, v176, v21, vcc
	v_cmp_le_i32_e32 vcc, v19, v130
	v_add_u32_e32 v19, 0xffffff89, v142
	v_max3_f32 v18, v18, v182, v183
	v_cndmask_b32_e32 v185, v176, v22, vcc
	v_cmp_le_i32_e32 vcc, v19, v130
	v_add_u32_e32 v19, 0xffffff8a, v142
	s_nop 0
	v_cndmask_b32_e32 v186, v176, v23, vcc
	v_cmp_le_i32_e32 vcc, v19, v130
	v_add_u32_e32 v19, 0xffffff8b, v142
	v_max3_f32 v18, v18, v185, v186
	v_cndmask_b32_e32 v190, v176, v24, vcc
	v_cmp_le_i32_e32 vcc, v19, v130
	v_add_u32_e32 v19, 0xffffff90, v142
	s_nop 0
	v_cndmask_b32_e32 v191, v176, v25, vcc
	v_cmp_le_i32_e32 vcc, v19, v130
	v_add_u32_e32 v19, 0xffffff91, v142
	v_max3_f32 v18, v18, v190, v191
	v_cndmask_b32_e32 v201, v176, v26, vcc
	v_cmp_le_i32_e32 vcc, v19, v130
	v_add_u32_e32 v19, 0xffffff92, v142
	s_nop 0
	v_cndmask_b32_e32 v195, v176, v27, vcc
	v_cmp_le_i32_e32 vcc, v19, v130
	v_add_u32_e32 v19, 0xffffff93, v142
	v_max3_f32 v18, v18, v201, v195
	v_cndmask_b32_e32 v202, v176, v28, vcc
	v_cmp_le_i32_e32 vcc, v19, v130
	v_add_u32_e32 v19, 0xffffff98, v142
	s_nop 0
	v_cndmask_b32_e32 v196, v176, v29, vcc
	v_cmp_le_i32_e32 vcc, v19, v130
	v_add_u32_e32 v19, 0xffffff99, v142
	v_max3_f32 v18, v18, v202, v196
	v_cndmask_b32_e32 v203, v176, v30, vcc
	v_cmp_le_i32_e32 vcc, v19, v130
	v_add_u32_e32 v19, 0xffffff9a, v142
	s_nop 0
	v_cndmask_b32_e32 v197, v176, v31, vcc
	v_cmp_le_i32_e32 vcc, v19, v130
	v_add_u32_e32 v19, 0xffffff9b, v142
	v_max3_f32 v18, v18, v203, v197
	v_cndmask_b32_e32 v204, v176, v32, vcc
	v_cmp_le_i32_e32 vcc, v19, v130
	v_add_u32_e32 v19, 0xffffffa0, v142
	s_nop 0
	v_cndmask_b32_e32 v198, v176, v33, vcc
	v_cmp_le_i32_e32 vcc, v19, v130
	v_max3_f32 v18, v18, v204, v198
	s_nop 0
	v_cndmask_b32_e32 v205, v176, v2, vcc
	v_add_u32_e32 v2, 0xffffffa1, v142
	v_cmp_le_i32_e32 vcc, v2, v130
	s_nop 1
	v_cndmask_b32_e32 v199, v176, v3, vcc
	v_add_u32_e32 v3, 0xffffffa2, v142
	v_cmp_le_i32_e32 vcc, v3, v130
	v_add_u32_e32 v3, 0xffffffa3, v142
	v_max3_f32 v2, v18, v205, v199
	v_cndmask_b32_e32 v200, v176, v4, vcc
	v_cmp_le_i32_e32 vcc, v3, v130
	v_add_u32_e32 v3, 0xffffffa8, v142
	v_and_b32_e32 v4, 64, v172
	v_cndmask_b32_e32 v193, v176, v5, vcc
	v_cmp_le_i32_e32 vcc, v3, v130
	v_add_u32_e32 v3, 0xffffffa9, v142
	v_max3_f32 v2, v2, v200, v193
	v_cndmask_b32_e32 v194, v176, v6, vcc
	v_cmp_le_i32_e32 vcc, v3, v130
	v_add_u32_e32 v3, 0xffffffaa, v142
	v_add_u32_e32 v4, 64, v4
	v_cndmask_b32_e32 v192, v176, v7, vcc
	v_cmp_le_i32_e32 vcc, v3, v130
	v_add_u32_e32 v3, 0xffffffab, v142
	v_max3_f32 v2, v2, v194, v192
	v_cndmask_b32_e32 v187, v176, v8, vcc
	v_cmp_le_i32_e32 vcc, v3, v130
	v_add_u32_e32 v3, 0xffffffb0, v142
	v_mov_b64_e32 v[18:19], v[34:35]
	v_cndmask_b32_e32 v188, v176, v9, vcc
	v_cmp_le_i32_e32 vcc, v3, v130
	v_add_u32_e32 v3, 0xffffffb1, v142
	v_max3_f32 v2, v2, v187, v188
	v_cndmask_b32_e32 v189, v176, v10, vcc
	v_cmp_le_i32_e32 vcc, v3, v130
	v_add_u32_e32 v3, 0xffffffb2, v142
	v_mov_b64_e32 v[20:21], v[36:37]
	v_cndmask_b32_e32 v184, v176, v11, vcc
	v_cmp_le_i32_e32 vcc, v3, v130
	v_add_u32_e32 v3, 0xffffffb3, v142
	v_max3_f32 v2, v2, v189, v184
	v_cndmask_b32_e32 v165, v176, v12, vcc
	v_cmp_le_i32_e32 vcc, v3, v130
	v_add_u32_e32 v3, 0xffffffb8, v142
	v_mov_b64_e32 v[22:23], v[38:39]
	v_cndmask_b32_e32 v164, v176, v13, vcc
	v_cmp_le_i32_e32 vcc, v3, v130
	v_add_u32_e32 v3, 0xffffffb9, v142
	v_max3_f32 v2, v2, v165, v164
	v_cndmask_b32_e32 v160, v176, v14, vcc
	v_cmp_le_i32_e32 vcc, v3, v130
	v_add_u32_e32 v3, 0xffffffba, v142
	v_mov_b64_e32 v[24:25], v[40:41]
	v_cndmask_b32_e32 v161, v176, v15, vcc
	v_cmp_le_i32_e32 vcc, v3, v130
	v_add_u32_e32 v3, 0xffffffbb, v142
	v_max3_f32 v2, v2, v160, v161
	v_cndmask_b32_e32 v162, v176, v16, vcc
	v_cmp_le_i32_e32 vcc, v3, v130
	v_xor_b32_e32 v3, 32, v172
	v_mov_b64_e32 v[26:27], v[42:43]
	v_cndmask_b32_e32 v159, v176, v17, vcc
	v_cmp_lt_i32_e32 vcc, v3, v4
	v_max3_f32 v2, v2, v162, v159
	v_mov_b64_e32 v[28:29], v[44:45]
	v_cndmask_b32_e32 v3, v172, v3, vcc
	v_lshlrev_b32_e32 v3, 2, v3
	v_mov_b32_e32 v3, v2
	s_nop 1
	v_permlane32_swap_b32 v3, v2
	v_mov_b64_e32 v[30:31], v[46:47]
	v_mov_b64_e32 v[32:33], v[48:49]
	v_mov_b32_e32 v142, v0
	s_waitcnt lgkmcnt(0)
	v_max3_f32 v157, v158, v2, v3
	v_mov_b64_e32 v[2:3], v[50:51]
	v_cmp_neq_f32_e32 vcc, v157, v158
	v_mov_b64_e32 v[4:5], v[52:53]
	v_mov_b64_e32 v[6:7], v[54:55]
	v_mov_b64_e32 v[8:9], v[56:57]
	v_mov_b64_e32 v[10:11], v[58:59]
	v_mov_b64_e32 v[12:13], v[60:61]
	v_mov_b64_e32 v[14:15], v[62:63]
	v_mov_b64_e32 v[16:17], v[64:65]
	s_cbranch_vccz .LBB0_251
	v_sub_f32_e32 v2, v158, v157
	v_mul_f32_e32 v2, 0x3e16c740, v2
	v_exp_f32_e32 v2, v2
	s_nop 0
	v_mul_f32_e32 v142, v0, v2
	v_pk_mul_f32 v[32:33], v[48:49], v[2:3] op_sel_hi:[1,0]
	v_pk_mul_f32 v[30:31], v[46:47], v[2:3] op_sel_hi:[1,0]
	v_pk_mul_f32 v[28:29], v[44:45], v[2:3] op_sel_hi:[1,0]
	v_pk_mul_f32 v[26:27], v[42:43], v[2:3] op_sel_hi:[1,0]
	v_pk_mul_f32 v[24:25], v[40:41], v[2:3] op_sel_hi:[1,0]
	v_pk_mul_f32 v[22:23], v[38:39], v[2:3] op_sel_hi:[1,0]
	v_pk_mul_f32 v[20:21], v[36:37], v[2:3] op_sel_hi:[1,0]
	v_pk_mul_f32 v[18:19], v[34:35], v[2:3] op_sel_hi:[1,0]
	v_pk_mul_f32 v[16:17], v[64:65], v[2:3] op_sel_hi:[1,0]
	v_pk_mul_f32 v[14:15], v[62:63], v[2:3] op_sel_hi:[1,0]
	v_pk_mul_f32 v[12:13], v[60:61], v[2:3] op_sel_hi:[1,0]
	v_pk_mul_f32 v[10:11], v[58:59], v[2:3] op_sel_hi:[1,0]
	v_pk_mul_f32 v[8:9], v[56:57], v[2:3] op_sel_hi:[1,0]
	v_pk_mul_f32 v[6:7], v[54:55], v[2:3] op_sel_hi:[1,0]
	v_pk_mul_f32 v[4:5], v[52:53], v[2:3] op_sel_hi:[1,0]
	v_pk_mul_f32 v[2:3], v[50:51], v[2:3] op_sel_hi:[1,0]

; #define MFMA32(a, b, c) __builtin_amdgcn_mfma_f32_32x32x16_bf16((a), (b), (c), 0, 0, 0)
; template <int DQK, bool WIN>
; DI void attn_item(const u16* __restrict__ Qb, int ldq, const u16* __restrict__ Kb, int ldk, const u16* __restrict__ Vtb, int qb,
;                   float qscale, float sink2, const u16* __restrict__ zb, int ldz, u16* __restrict__ ob, int ldo, u16* lds) {
;     ...
;       f32x16 st[2];
; #pragma unroll
;       for (int kb = 0; kb < 2; ++kb) {
; #pragma unroll
;         for (int i = 0; i < 16; ++i) st[kb][i] = 0.f;
; #pragma unroll
;         for (int s = 0; s < NKS; ++s) {
;           bf16x8 a = *(const bf16x8*)(ks + (kb * 32 + r) * KST + 16 * s + 8 * hh);
;           st[kb] = MFMA32(a, qf[s], st[kb]);
;         }
;       }
;       float mx = -INFINITY;
; #pragma unroll
;       for (int kb = 0; kb < 2; ++kb)
; #pragma unroll
;         for (int i = 0; i < 16; ++i) {
;           float v = st[kb][i];
;           if (MASK) {
;             int kg = k0 + kb * 32 + (i & 3) + 8 * (i >> 2) + 4 * hh;
;             bool ok = kg <= qrow;
;             if (WIN) ok = ok && (qrow - kg < 128);
;             v = ok ? v : -INFINITY;
;             st[kb][i] = v;
;           }
;           mx = fmaxf(mx, v);
;         }
;       mx = fmaxf(mx, __shfl_xor(mx, 32));
;       const float mn = fmaxf(m, mx);
;       if (__any(mn != m)) {
;         const float alpha = __builtin_amdgcn_exp2f((m - mn) * qscale);
;         lsum *= alpha;
; #pragma unroll
;         for (int i = 0; i < 16; ++i) { o[0][i] *= alpha; o[1][i] *= alpha; }
;       }
.LBB0_258:
	s_and_saveexec_b64 s[24:25], s[8:9]
	s_cbranch_execz .LBB0_262
	ds_read_b128 v[182:185], v155 offset:22528
	ds_read_b128 v[186:189], v155 offset:22560
	ds_read_b128 v[190:193], v155 offset:22592
	ds_read_b128 v[194:197], v155 offset:29216
	ds_read_b128 v[198:201], v155 offset:22624
	ds_read_b128 v[202:205], v155 offset:22656
	ds_read_b128 v[206:209], v155 offset:22688
	ds_read_b128 v[210:213], v155 offset:29184
	ds_read_b128 v[214:217], v155 offset:29248
	ds_read_b128 v[218:221], v155 offset:29280
	ds_read_b128 v[222:225], v155 offset:29312
	ds_read_b128 v[226:229], v155 offset:29344
	s_nop 7
	v_and_b32_e32 v159, 64, v172
	v_xor_b32_e32 v157, 32, v172
	v_add_u32_e32 v159, 64, v159
	s_waitcnt lgkmcnt(11)
	v_mfma_f32_32x32x16_bf16 v[18:33], v[182:185], v[66:69], 0
	v_cmp_lt_i32_e32 vcc, v157, v159
	s_nop 1
	v_cndmask_b32_e32 v157, v172, v157, vcc
	v_lshlrev_b32_e32 v157, 2, v157
	s_waitcnt lgkmcnt(10)
	v_mfma_f32_32x32x16_bf16 v[18:33], v[186:189], v[70:73], v[18:33]
	s_waitcnt lgkmcnt(9)
	v_mfma_f32_32x32x16_bf16 v[18:33], v[190:193], v[74:77], v[18:33]
	s_waitcnt lgkmcnt(7)
	v_mfma_f32_32x32x16_bf16 v[18:33], v[198:201], v[78:81], v[18:33]
	s_waitcnt lgkmcnt(6)
	v_mfma_f32_32x32x16_bf16 v[18:33], v[202:205], v[82:85], v[18:33]
	s_waitcnt lgkmcnt(5)
	v_mfma_f32_32x32x16_bf16 v[18:33], v[206:209], v[86:89], v[18:33]
	s_waitcnt lgkmcnt(4)
	v_mfma_f32_32x32x16_bf16 v[2:17], v[210:213], v[66:69], 0
	s_nop 8
	s_nop 0
	v_max3_f32 v142, v18, s94, v19
	v_max3_f32 v142, v142, v20, v21
	v_max3_f32 v142, v142, v22, v23
	v_max3_f32 v142, v142, v24, v25
	v_max3_f32 v142, v142, v26, v27
	v_max3_f32 v142, v142, v28, v29
	v_max3_f32 v142, v142, v30, v31
	v_mfma_f32_32x32x16_bf16 v[2:17], v[194:197], v[70:73], v[2:17]
	v_max3_f32 v142, v142, v32, v33
	s_waitcnt lgkmcnt(3)
	v_mfma_f32_32x32x16_bf16 v[2:17], v[214:217], v[74:77], v[2:17]
	s_waitcnt lgkmcnt(2)
	v_mfma_f32_32x32x16_bf16 v[2:17], v[218:221], v[78:81], v[2:17]
	s_waitcnt lgkmcnt(1)
	v_mfma_f32_32x32x16_bf16 v[2:17], v[222:225], v[82:85], v[2:17]
	s_waitcnt lgkmcnt(0)
	v_mfma_f32_32x32x16_bf16 v[2:17], v[226:229], v[86:89], v[2:17]
	s_nop 11
	v_max3_f32 v142, v142, v2, v3
	v_max3_f32 v142, v142, v4, v5
	v_max3_f32 v142, v142, v6, v7
	v_max3_f32 v142, v142, v8, v9
	v_max3_f32 v142, v142, v10, v11
	v_max3_f32 v142, v142, v12, v13
	v_max3_f32 v142, v142, v14, v15
	v_max3_f32 v142, v142, v16, v17
	v_mov_b32_e32 v157, v142
	s_nop 1
	v_permlane32_swap_b32 v157, v142
	s_waitcnt lgkmcnt(0)
	v_max3_f32 v142, v158, v142, v157
	v_cmp_neq_f32_e32 vcc, v142, v158
	s_cbranch_vccz .LBB0_261
	v_sub_f32_e32 v157, v158, v142
	v_mul_f32_e32 v157, 0x3e16c740, v157
	v_exp_f32_e32 v158, v157
	s_nop 0
	v_mul_f32_e32 v0, v0, v158
	v_pk_mul_f32 v[48:49], v[48:49], v[158:159] op_sel_hi:[1,0]
	v_pk_mul_f32 v[46:47], v[46:47], v[158:159] op_sel_hi:[1,0]
	v_pk_mul_f32 v[44:45], v[44:45], v[158:159] op_sel_hi:[1,0]
	v_pk_mul_f32 v[42:43], v[42:43], v[158:159] op_sel_hi:[1,0]
	v_pk_mul_f32 v[40:41], v[40:41], v[158:159] op_sel_hi:[1,0]
	v_pk_mul_f32 v[38:39], v[38:39], v[158:159] op_sel_hi:[1,0]
	v_pk_mul_f32 v[36:37], v[36:37], v[158:159] op_sel_hi:[1,0]
	v_pk_mul_f32 v[34:35], v[34:35], v[158:159] op_sel_hi:[1,0]
	v_pk_mul_f32 v[64:65], v[64:65], v[158:159] op_sel_hi:[1,0]
	v_pk_mul_f32 v[62:63], v[62:63], v[158:159] op_sel_hi:[1,0]
	v_pk_mul_f32 v[60:61], v[60:61], v[158:159] op_sel_hi:[1,0]
	v_pk_mul_f32 v[58:59], v[58:59], v[158:159] op_sel_hi:[1,0]
	v_pk_mul_f32 v[56:57], v[56:57], v[158:159] op_sel_hi:[1,0]
	v_pk_mul_f32 v[54:55], v[54:55], v[158:159] op_sel_hi:[1,0]
	v_pk_mul_f32 v[52:53], v[52:53], v[158:159] op_sel_hi:[1,0]
	v_pk_mul_f32 v[50:51], v[50:51], v[158:159] op_sel_hi:[1,0]

; #define MFMA32(a, b, c) __builtin_amdgcn_mfma_f32_32x32x16_bf16((a), (b), (c), 0, 0, 0)
; template <int DQK, bool WIN>
; DI void attn_item(const u16* __restrict__ Qb, int ldq, const u16* __restrict__ Kb, int ldk, const u16* __restrict__ Vtb, int qb,
;                   float qscale, float sink2, const u16* __restrict__ zb, int ldz, u16* __restrict__ ob, int ldo, u16* lds) {
;     ...
;     bool active = (k0 <= q0 + 31);
;     if (WIN) active = active && (k0 + 63 >= q0 - 127);
;     if (active) {
;       f32x16 st[2];
; #pragma unroll
;       for (int kb = 0; kb < 2; ++kb) {
; #pragma unroll
;         for (int i = 0; i < 16; ++i) st[kb][i] = 0.f;
; #pragma unroll
;         for (int s = 0; s < NKS; ++s) {
;           bf16x8 a = *(const bf16x8*)(ks + (kb * 32 + r) * KST + 16 * s + 8 * hh);
;           st[kb] = MFMA32(a, qf[s], st[kb]);
;         }
;       }
;       float mx = -INFINITY;
; #pragma unroll
;       for (int kb = 0; kb < 2; ++kb)
; #pragma unroll
;         for (int i = 0; i < 16; ++i) {
;           float v = st[kb][i];
;           if (MASK) {
;             int kg = k0 + kb * 32 + (i & 3) + 8 * (i >> 2) + 4 * hh;
;             bool ok = kg <= qrow;
;             if (WIN) ok = ok && (qrow - kg < 128);
;             v = ok ? v : -INFINITY;
;             st[kb][i] = v;
;           }
;           mx = fmaxf(mx, v);
.LBB0_317:
	s_add_i32 s0, s26, 0xffffff40
	v_cmp_le_i32_e32 vcc, s0, v137
	s_add_i32 s0, s26, 0xffffff7f
	v_cmp_ge_i32_e64 s[8:9], s0, v138
	s_and_b64 s[0:1], vcc, s[8:9]
	v_add_u32_e32 v143, s26, v0
	s_and_saveexec_b64 s[34:35], s[0:1]
	s_cbranch_execz .LBB0_321
	ds_read_b128 v[152:155], v139
	ds_read_b128 v[164:167], v139 offset:32
	ds_read_b128 v[182:185], v139 offset:64
	ds_read_b128 v[186:189], v139 offset:4640
	ds_read_b128 v[190:193], v139 offset:96
	ds_read_b128 v[194:197], v139 offset:4608
	ds_read_b128 v[198:201], v139 offset:4672
	ds_read_b128 v[202:205], v139 offset:4704
	v_add_u32_e32 v145, 0xffffff40, v143
	v_cmp_le_i32_e64 s[8:9], v145, v114
	s_movk_i32 s0, 0xff7f
	s_waitcnt lgkmcnt(7)
	v_mfma_f32_32x32x16_bf16 v[50:65], v[152:155], v[66:69], 0
	s_waitcnt lgkmcnt(6)
	v_mfma_f32_32x32x16_bf16 v[50:65], v[164:167], v[70:73], v[50:65]
	s_waitcnt lgkmcnt(5)
	v_mfma_f32_32x32x16_bf16 v[50:65], v[182:185], v[74:77], v[50:65]
	s_waitcnt lgkmcnt(3)
	v_mfma_f32_32x32x16_bf16 v[50:65], v[190:193], v[78:81], v[50:65]
	s_waitcnt lgkmcnt(2)
	v_mfma_f32_32x32x16_bf16 v[34:49], v[194:197], v[66:69], 0
	v_mfma_f32_32x32x16_bf16 v[34:49], v[186:189], v[70:73], v[34:49]
	s_waitcnt lgkmcnt(1)
	v_mfma_f32_32x32x16_bf16 v[34:49], v[198:201], v[74:77], v[34:49]
	s_waitcnt lgkmcnt(0)
	v_mfma_f32_32x32x16_bf16 v[34:49], v[202:205], v[78:81], v[34:49]
	v_add_u32_e32 v146, 59, v141
	v_cmp_gt_i32_e32 vcc, s93, v146
	s_and_b64 vcc, s[8:9], vcc
	v_add_u32_e32 v146, 0xffffff42, v143
	s_nop 0
	v_cndmask_b32_e32 v50, v176, v50, vcc
	v_cmp_lt_i32_e32 vcc, v145, v114
	v_add_u32_e32 v145, s26, v142
	v_add_u32_e32 v145, 0xffffff40, v145
	v_cmp_lt_i32_e64 s[8:9], s0, v145
	s_and_b64 vcc, vcc, s[8:9]
	v_add_u32_e32 v147, 57, v141
	v_cndmask_b32_e32 v51, v176, v51, vcc
	v_cmp_gt_i32_e32 vcc, s93, v147
	v_cmp_le_i32_e64 s[8:9], v146, v114
	s_and_b64 vcc, s[8:9], vcc
	v_add_u32_e32 v146, 0xffffff43, v143
	v_add_u32_e32 v147, 56, v141
	v_cndmask_b32_e32 v52, v176, v52, vcc
	v_cmp_gt_i32_e32 vcc, s93, v147
	v_cmp_le_i32_e64 s[8:9], v146, v114
	s_and_b64 vcc, s[8:9], vcc
	v_add_u32_e32 v146, 0xffffff48, v143
	v_add_u32_e32 v147, 51, v141
	v_cndmask_b32_e32 v53, v176, v53, vcc
	v_cmp_gt_i32_e32 vcc, s93, v147
	v_cmp_le_i32_e64 s[8:9], v146, v114
	s_and_b64 vcc, s[8:9], vcc
	v_cndmask_b32_e32 v148, v176, v54, vcc
	v_add_u32_e32 v54, 0xffffff49, v143
	v_add_u32_e32 v146, 50, v141
	v_cmp_gt_i32_e32 vcc, s93, v146
	v_cmp_le_i32_e64 s[8:9], v54, v114
	v_max3_f32 v145, v50, s94, v51
	s_and_b64 vcc, s[8:9], vcc
	v_max3_f32 v145, v145, v52, v53
	v_cndmask_b32_e32 v147, v176, v55, vcc
	v_max3_f32 v54, v145, v148, v147
	v_add_u32_e32 v55, 0xffffff4a, v143
	v_add_u32_e32 v145, 49, v141
	v_cmp_gt_i32_e32 vcc, s93, v145
	v_cmp_le_i32_e64 s[8:9], v55, v114
	s_and_b64 vcc, s[8:9], vcc
	v_cndmask_b32_e32 v149, v176, v56, vcc
	v_add_u32_e32 v55, 0xffffff4b, v143
	v_add_u32_e32 v56, 48, v141
	v_cmp_gt_i32_e32 vcc, s93, v56
	v_cmp_le_i32_e64 s[8:9], v55, v114
	s_and_b64 vcc, s[8:9], vcc
	v_add_u32_e32 v55, 0xffffff50, v143
	v_add_u32_e32 v56, 43, v141
	v_cndmask_b32_e32 v150, v176, v57, vcc
	v_cmp_gt_i32_e32 vcc, s93, v56
	v_cmp_le_i32_e64 s[8:9], v55, v114
	s_and_b64 vcc, s[8:9], vcc
	v_add_u32_e32 v55, 0xffffff51, v143
	v_add_u32_e32 v56, 42, v141
	v_cndmask_b32_e32 v151, v176, v58, vcc
	v_cmp_gt_i32_e32 vcc, s93, v56
	v_cmp_le_i32_e64 s[8:9], v55, v114
	s_and_b64 vcc, s[8:9], vcc
	v_add_u32_e32 v55, 0xffffff52, v143
	v_add_u32_e32 v56, 41, v141
	v_cndmask_b32_e32 v145, v176, v59, vcc
	v_cmp_gt_i32_e32 vcc, s93, v56
	v_cmp_le_i32_e64 s[8:9], v55, v114
	s_and_b64 vcc, s[8:9], vcc
	v_add_u32_e32 v55, 0xffffff53, v143
	v_add_u32_e32 v56, 40, v141
	v_cndmask_b32_e32 v146, v176, v60, vcc
	v_cmp_gt_i32_e32 vcc, s93, v56
	v_cmp_le_i32_e64 s[8:9], v55, v114
	s_and_b64 vcc, s[8:9], vcc
	v_add_u32_e32 v55, 0xffffff58, v143
	v_add_u32_e32 v56, 35, v141
	v_cndmask_b32_e32 v60, v176, v61, vcc
	v_cmp_gt_i32_e32 vcc, s93, v56
	v_cmp_le_i32_e64 s[8:9], v55, v114
	s_and_b64 vcc, s[8:9], vcc
	v_add_u32_e32 v55, 0xffffff59, v143
	v_add_u32_e32 v56, 34, v141
	v_cndmask_b32_e32 v61, v176, v62, vcc
	v_cmp_gt_i32_e32 vcc, s93, v56
	v_cmp_le_i32_e64 s[8:9], v55, v114
	s_and_b64 vcc, s[8:9], vcc
	v_add_u32_e32 v55, 0xffffff5a, v143
	v_add_u32_e32 v56, 33, v141
	v_cndmask_b32_e32 v58, v176, v63, vcc
	v_cmp_gt_i32_e32 vcc, s93, v56
	v_cmp_le_i32_e64 s[8:9], v55, v114
	v_max3_f32 v54, v54, v149, v150
	s_and_b64 vcc, s[8:9], vcc
	v_add_u32_e32 v55, 0xffffff5b, v143
	v_add_u32_e32 v56, 32, v141
	v_max3_f32 v54, v54, v151, v145
	v_cndmask_b32_e32 v59, v176, v64, vcc
	v_cmp_gt_i32_e32 vcc, s93, v56
	v_cmp_le_i32_e64 s[8:9], v55, v114
	v_max3_f32 v54, v54, v146, v60
	s_and_b64 vcc, s[8:9], vcc
	v_max3_f32 v54, v54, v61, v58
	v_cndmask_b32_e32 v56, v176, v65, vcc
	v_max3_f32 v55, v54, v59, v56
	v_add_u32_e32 v54, 0xffffff60, v143
; template <int DQK, bool WIN>
; DI void attn_item(const u16* __restrict__ Qb, int ldq, const u16* __restrict__ Kb, int ldk, const u16* __restrict__ Vtb, int qb,
;                   float qscale, float sink2, const u16* __restrict__ zb, int ldz, u16* __restrict__ ob, int ldo, u16* lds) {
;     ...
;           if (MASK) {
;             int kg = k0 + kb * 32 + (i & 3) + 8 * (i >> 2) + 4 * hh;
;             bool ok = kg <= qrow;
;             if (WIN) ok = ok && (qrow - kg < 128);
;             v = ok ? v : -INFINITY;
;             st[kb][i] = v;
;           }
;           mx = fmaxf(mx, v);
;         }
;       mx = fmaxf(mx, __shfl_xor(mx, 32));
;       const float mn = fmaxf(m, mx);
;       if (__any(mn != m)) {
;         const float alpha = __builtin_amdgcn_exp2f((m - mn) * qscale);
;         lsum *= alpha;
; #pragma unroll
;         for (int i = 0; i < 16; ++i) { o[0][i] *= alpha; o[1][i] *= alpha; }
;       }
	v_add_u32_e32 v57, 27, v141
	v_cmp_gt_i32_e32 vcc, s93, v57
	v_cmp_le_i32_e64 s[8:9], v54, v114
	s_and_b64 vcc, s[8:9], vcc
	v_cndmask_b32_e32 v57, v176, v34, vcc
	v_add_u32_e32 v34, 0xffffff61, v143
	v_add_u32_e32 v54, 26, v141
	v_cmp_gt_i32_e32 vcc, s93, v54
	v_cmp_le_i32_e64 s[8:9], v34, v114
	s_and_b64 vcc, s[8:9], vcc
	v_cndmask_b32_e32 v54, v176, v35, vcc
	v_max3_f32 v34, v55, v57, v54
	v_add_u32_e32 v35, 0xffffff62, v143
	v_add_u32_e32 v55, 25, v141
	v_cmp_gt_i32_e32 vcc, s93, v55
	v_cmp_le_i32_e64 s[8:9], v35, v114
	s_and_b64 vcc, s[8:9], vcc
	v_cndmask_b32_e32 v55, v176, v36, vcc
	v_add_u32_e32 v35, 0xffffff63, v143
	v_add_u32_e32 v36, 24, v141
	v_cmp_gt_i32_e32 vcc, s93, v36
	v_cmp_le_i32_e64 s[8:9], v35, v114
	s_and_b64 vcc, s[8:9], vcc
	v_cndmask_b32_e32 v36, v176, v37, vcc
	v_add_u32_e32 v35, 0xffffff68, v143
	v_add_u32_e32 v37, 19, v141
	v_cmp_gt_i32_e32 vcc, s93, v37
	v_cmp_le_i32_e64 s[8:9], v35, v114
	s_and_b64 vcc, s[8:9], vcc
	v_cndmask_b32_e32 v37, v176, v38, vcc
	v_add_u32_e32 v35, 0xffffff69, v143
	v_add_u32_e32 v38, 18, v141
	v_cmp_gt_i32_e32 vcc, s93, v38
	v_cmp_le_i32_e64 s[8:9], v35, v114
	s_and_b64 vcc, s[8:9], vcc
	v_cndmask_b32_e32 v35, v176, v39, vcc
	v_add_u32_e32 v38, 0xffffff6a, v143
	v_add_u32_e32 v39, 17, v141
	v_cmp_gt_i32_e32 vcc, s93, v39
	v_cmp_le_i32_e64 s[8:9], v38, v114
	s_and_b64 vcc, s[8:9], vcc
	v_cndmask_b32_e32 v38, v176, v40, vcc
	v_add_u32_e32 v39, 0xffffff6b, v143
	v_add_u32_e32 v40, 16, v141
	v_cmp_gt_i32_e32 vcc, s93, v40
	v_cmp_le_i32_e64 s[8:9], v39, v114
	s_and_b64 vcc, s[8:9], vcc
	v_cndmask_b32_e32 v39, v176, v41, vcc
	v_add_u32_e32 v40, 0xffffff70, v143
	v_add_u32_e32 v41, 11, v141
	v_cmp_gt_i32_e32 vcc, s93, v41
	v_cmp_le_i32_e64 s[8:9], v40, v114
	s_and_b64 vcc, s[8:9], vcc
	v_cndmask_b32_e32 v40, v176, v42, vcc
	v_add_u32_e32 v41, 0xffffff71, v143
	v_add_u32_e32 v42, 10, v141
	v_cmp_gt_i32_e32 vcc, s93, v42
	v_cmp_le_i32_e64 s[8:9], v41, v114
	s_and_b64 vcc, s[8:9], vcc
	v_cndmask_b32_e32 v41, v176, v43, vcc
	v_add_u32_e32 v42, 0xffffff72, v143
	v_add_u32_e32 v43, 9, v141
	v_cmp_gt_i32_e32 vcc, s93, v43
	v_cmp_le_i32_e64 s[8:9], v42, v114
	s_and_b64 vcc, s[8:9], vcc
	v_cndmask_b32_e32 v42, v176, v44, vcc
	v_add_u32_e32 v43, 0xffffff73, v143
	v_add_u32_e32 v44, 8, v141
	v_cmp_gt_i32_e32 vcc, s93, v44
	v_cmp_le_i32_e64 s[8:9], v43, v114
	s_and_b64 vcc, s[8:9], vcc
	v_cndmask_b32_e32 v43, v176, v45, vcc
	v_add_u32_e32 v44, 0xffffff78, v143
	v_add_u32_e32 v45, 3, v141
	v_cmp_gt_i32_e32 vcc, s93, v45
	v_cmp_le_i32_e64 s[8:9], v44, v114
	s_and_b64 vcc, s[8:9], vcc
	v_cndmask_b32_e32 v44, v176, v46, vcc
	v_add_u32_e32 v45, 0xffffff79, v143
	v_add_u32_e32 v46, 2, v141
	v_cmp_gt_i32_e32 vcc, s93, v46
	v_cmp_le_i32_e64 s[8:9], v45, v114
	s_and_b64 vcc, s[8:9], vcc
	v_cndmask_b32_e32 v45, v176, v47, vcc
	v_add_u32_e32 v46, 0xffffff7a, v143
	v_add_u32_e32 v47, 1, v141
	v_cmp_gt_i32_e32 vcc, s93, v47
	v_cmp_le_i32_e64 s[8:9], v46, v114
	s_and_b64 vcc, s[8:9], vcc
	v_add_u32_e32 v47, 0xffffff7b, v143
	v_max3_f32 v34, v34, v55, v36
	v_cndmask_b32_e32 v46, v176, v48, vcc
	v_cmp_gt_i32_e32 vcc, s93, v141
	v_cmp_le_i32_e64 s[8:9], v47, v114
	v_max3_f32 v34, v34, v37, v35
	s_and_b64 vcc, s[8:9], vcc
	v_max3_f32 v34, v34, v38, v39
	v_cndmask_b32_e32 v47, v176, v49, vcc
	v_and_b32_e32 v49, 64, v172
	v_max3_f32 v34, v34, v40, v41
	v_xor_b32_e32 v48, 32, v172
	v_add_u32_e32 v49, 64, v49
	v_max3_f32 v34, v34, v42, v43
	v_cmp_lt_i32_e32 vcc, v48, v49
	v_max3_f32 v34, v34, v44, v45
	v_max3_f32 v34, v34, v46, v47
	v_cndmask_b32_e32 v48, v172, v48, vcc
	v_lshlrev_b32_e32 v48, 2, v48
	v_mov_b32_e32 v48, v34
	s_nop 1
	v_permlane32_swap_b32 v48, v34
	s_waitcnt lgkmcnt(0)
	v_max3_f32 v34, v144, v34, v48
	v_cmp_neq_f32_e32 vcc, v34, v144
	s_cbranch_vccz .LBB0_320
	v_sub_f32_e32 v48, v144, v34
	v_mul_f32_e32 v48, 0x3e38aa3b, v48
	v_exp_f32_e32 v48, v48
	s_nop 0
	v_mul_f32_e32 v116, v116, v48
	v_pk_mul_f32 v[32:33], v[32:33], v[48:49] op_sel_hi:[1,0]
	v_pk_mul_f32 v[30:31], v[30:31], v[48:49] op_sel_hi:[1,0]
	v_pk_mul_f32 v[28:29], v[28:29], v[48:49] op_sel_hi:[1,0]
	v_pk_mul_f32 v[26:27], v[26:27], v[48:49] op_sel_hi:[1,0]
	v_pk_mul_f32 v[24:25], v[24:25], v[48:49] op_sel_hi:[1,0]
	v_pk_mul_f32 v[22:23], v[22:23], v[48:49] op_sel_hi:[1,0]
	v_pk_mul_f32 v[20:21], v[20:21], v[48:49] op_sel_hi:[1,0]
	v_pk_mul_f32 v[18:19], v[18:19], v[48:49] op_sel_hi:[1,0]
	v_pk_mul_f32 v[16:17], v[16:17], v[48:49] op_sel_hi:[1,0]
	v_pk_mul_f32 v[14:15], v[14:15], v[48:49] op_sel_hi:[1,0]
	v_pk_mul_f32 v[12:13], v[12:13], v[48:49] op_sel_hi:[1,0]
	v_pk_mul_f32 v[10:11], v[10:11], v[48:49] op_sel_hi:[1,0]
	v_pk_mul_f32 v[8:9], v[8:9], v[48:49] op_sel_hi:[1,0]
	v_pk_mul_f32 v[6:7], v[6:7], v[48:49] op_sel_hi:[1,0]
	v_pk_mul_f32 v[4:5], v[4:5], v[48:49] op_sel_hi:[1,0]
	v_pk_mul_f32 v[2:3], v[2:3], v[48:49] op_sel_hi:[1,0]

; #define MFMA32(a, b, c) __builtin_amdgcn_mfma_f32_32x32x16_bf16((a), (b), (c), 0, 0, 0)
; template <int DQK, bool WIN>
; DI void attn_item(const u16* __restrict__ Qb, int ldq, const u16* __restrict__ Kb, int ldk, const u16* __restrict__ Vtb, int qb,
;                   float qscale, float sink2, const u16* __restrict__ zb, int ldz, u16* __restrict__ ob, int ldo, u16* lds) {
;     ...
;     bool active = (k0 <= q0 + 31);
;     if (WIN) active = active && (k0 + 63 >= q0 - 127);
;     if (active) {
;       f32x16 st[2];
; #pragma unroll
;       for (int kb = 0; kb < 2; ++kb) {
; #pragma unroll
;         for (int i = 0; i < 16; ++i) st[kb][i] = 0.f;
; #pragma unroll
;         for (int s = 0; s < NKS; ++s) {
;           bf16x8 a = *(const bf16x8*)(ks + (kb * 32 + r) * KST + 16 * s + 8 * hh);
;           st[kb] = MFMA32(a, qf[s], st[kb]);
;         }
;       }
;       float mx = -INFINITY;
; #pragma unroll
;       for (int kb = 0; kb < 2; ++kb)
; #pragma unroll
;         for (int i = 0; i < 16; ++i) {
;           float v = st[kb][i];
;           if (MASK) {
;             int kg = k0 + kb * 32 + (i & 3) + 8 * (i >> 2) + 4 * hh;
;             bool ok = kg <= qrow;
;             if (WIN) ok = ok && (qrow - kg < 128);
;             v = ok ? v : -INFINITY;
;             st[kb][i] = v;
;           }
;           mx = fmaxf(mx, v);
.LBB0_323:
	s_add_i32 s0, s26, 0xffffff80
	v_cmp_le_i32_e32 vcc, s0, v137
	s_add_i32 s0, s26, 0xffffffbf
	v_cmp_ge_i32_e64 s[8:9], s0, v138
	s_and_b64 s[0:1], vcc, s[8:9]
	s_and_saveexec_b64 s[34:35], s[0:1]
	s_cbranch_execz .LBB0_327
	ds_read_b128 v[152:155], v139 offset:18432
	ds_read_b128 v[164:167], v139 offset:18464
	ds_read_b128 v[182:185], v139 offset:18496
	ds_read_b128 v[186:189], v139 offset:23072
	ds_read_b128 v[190:193], v139 offset:18528
	ds_read_b128 v[194:197], v139 offset:23040
	ds_read_b128 v[198:201], v139 offset:23104
	ds_read_b128 v[202:205], v139 offset:23136
	v_add_u32_e32 v145, 0xffffff80, v143
	v_cmp_le_i32_e64 s[8:9], v145, v114
	v_add_u32_e32 v145, 0xffffff81, v143
	s_waitcnt lgkmcnt(7)
	v_mfma_f32_32x32x16_bf16 v[50:65], v[152:155], v[66:69], 0
	s_waitcnt lgkmcnt(6)
	v_mfma_f32_32x32x16_bf16 v[50:65], v[164:167], v[70:73], v[50:65]
	s_waitcnt lgkmcnt(5)
	v_mfma_f32_32x32x16_bf16 v[50:65], v[182:185], v[74:77], v[50:65]
	s_waitcnt lgkmcnt(3)
	v_mfma_f32_32x32x16_bf16 v[50:65], v[190:193], v[78:81], v[50:65]
	s_waitcnt lgkmcnt(2)
	v_mfma_f32_32x32x16_bf16 v[34:49], v[194:197], v[66:69], 0
	v_mfma_f32_32x32x16_bf16 v[34:49], v[186:189], v[70:73], v[34:49]
	s_waitcnt lgkmcnt(1)
	v_mfma_f32_32x32x16_bf16 v[34:49], v[198:201], v[74:77], v[34:49]
	s_waitcnt lgkmcnt(0)
	v_mfma_f32_32x32x16_bf16 v[34:49], v[202:205], v[78:81], v[34:49]
	v_add_u32_e32 v146, -5, v141
	v_cmp_gt_i32_e32 vcc, s93, v146
	s_and_b64 vcc, s[8:9], vcc
	v_add_u32_e32 v146, -6, v141
	s_nop 0
	v_cndmask_b32_e32 v50, v176, v50, vcc
	v_cmp_gt_i32_e32 vcc, s93, v146
	v_cmp_le_i32_e64 s[8:9], v145, v114
	s_and_b64 vcc, s[8:9], vcc
	v_add_u32_e32 v146, 0xffffff82, v143
	v_add_u32_e32 v147, -7, v141
	v_cndmask_b32_e32 v51, v176, v51, vcc
	v_cmp_gt_i32_e32 vcc, s93, v147
	v_cmp_le_i32_e64 s[8:9], v146, v114
	s_and_b64 vcc, s[8:9], vcc
	v_add_u32_e32 v146, 0xffffff83, v143
	v_add_u32_e32 v147, -8, v141
	v_cndmask_b32_e32 v52, v176, v52, vcc
	v_cmp_gt_i32_e32 vcc, s93, v147
	v_cmp_le_i32_e64 s[8:9], v146, v114
	s_and_b64 vcc, s[8:9], vcc
	v_add_u32_e32 v146, 0xffffff88, v143
	v_add_u32_e32 v147, -13, v141
	v_cndmask_b32_e32 v53, v176, v53, vcc
	v_cmp_gt_i32_e32 vcc, s93, v147
	v_cmp_le_i32_e64 s[8:9], v146, v114
	s_and_b64 vcc, s[8:9], vcc
	v_cndmask_b32_e32 v148, v176, v54, vcc
	v_add_u32_e32 v54, 0xffffff89, v143
	v_add_u32_e32 v146, -14, v141
	v_cmp_gt_i32_e32 vcc, s93, v146
	v_cmp_le_i32_e64 s[8:9], v54, v114
	v_max3_f32 v145, v50, s94, v51
	s_and_b64 vcc, s[8:9], vcc
	v_max3_f32 v145, v145, v52, v53
	v_cndmask_b32_e32 v147, v176, v55, vcc
	v_max3_f32 v54, v145, v148, v147
	v_add_u32_e32 v55, 0xffffff8a, v143
	v_add_u32_e32 v145, -15, v141
	v_cmp_gt_i32_e32 vcc, s93, v145
	v_cmp_le_i32_e64 s[8:9], v55, v114
	s_and_b64 vcc, s[8:9], vcc
	v_cndmask_b32_e32 v149, v176, v56, vcc
	v_add_u32_e32 v55, 0xffffff8b, v143
	v_add_u32_e32 v56, -16, v141
	v_cmp_gt_i32_e32 vcc, s93, v56
	v_cmp_le_i32_e64 s[8:9], v55, v114
	s_and_b64 vcc, s[8:9], vcc
	v_add_u32_e32 v55, 0xffffff90, v143
	v_subrev_u32_e32 v56, 21, v141
	v_cndmask_b32_e32 v150, v176, v57, vcc
	v_cmp_gt_i32_e32 vcc, s93, v56
	v_cmp_le_i32_e64 s[8:9], v55, v114
	s_and_b64 vcc, s[8:9], vcc
	v_add_u32_e32 v55, 0xffffff91, v143
	v_subrev_u32_e32 v56, 22, v141
	v_cndmask_b32_e32 v151, v176, v58, vcc
	v_cmp_gt_i32_e32 vcc, s93, v56
	v_cmp_le_i32_e64 s[8:9], v55, v114
	s_and_b64 vcc, s[8:9], vcc
	v_add_u32_e32 v55, 0xffffff92, v143
	v_subrev_u32_e32 v56, 23, v141
	v_cndmask_b32_e32 v145, v176, v59, vcc
	v_cmp_gt_i32_e32 vcc, s93, v56
	v_cmp_le_i32_e64 s[8:9], v55, v114
	s_and_b64 vcc, s[8:9], vcc
	v_add_u32_e32 v55, 0xffffff93, v143
	v_subrev_u32_e32 v56, 24, v141
	v_cndmask_b32_e32 v146, v176, v60, vcc
	v_cmp_gt_i32_e32 vcc, s93, v56
	v_cmp_le_i32_e64 s[8:9], v55, v114
	s_and_b64 vcc, s[8:9], vcc
	v_add_u32_e32 v55, 0xffffff98, v143
	v_subrev_u32_e32 v56, 29, v141
	v_cndmask_b32_e32 v60, v176, v61, vcc
	v_cmp_gt_i32_e32 vcc, s93, v56
	v_cmp_le_i32_e64 s[8:9], v55, v114
	s_and_b64 vcc, s[8:9], vcc
	v_add_u32_e32 v55, 0xffffff99, v143
	v_subrev_u32_e32 v56, 30, v141
	v_cndmask_b32_e32 v61, v176, v62, vcc
	v_cmp_gt_i32_e32 vcc, s93, v56
	v_cmp_le_i32_e64 s[8:9], v55, v114
	s_and_b64 vcc, s[8:9], vcc
	v_add_u32_e32 v55, 0xffffff9a, v143
	v_subrev_u32_e32 v56, 31, v141
	v_cndmask_b32_e32 v58, v176, v63, vcc
	v_cmp_gt_i32_e32 vcc, s93, v56
	v_cmp_le_i32_e64 s[8:9], v55, v114
	v_max3_f32 v54, v54, v149, v150
	s_and_b64 vcc, s[8:9], vcc
	v_add_u32_e32 v55, 0xffffff9b, v143
	v_subrev_u32_e32 v56, 32, v141
	v_max3_f32 v54, v54, v151, v145
	v_cndmask_b32_e32 v59, v176, v64, vcc
	v_cmp_gt_i32_e32 vcc, s93, v56
	v_cmp_le_i32_e64 s[8:9], v55, v114
	v_max3_f32 v54, v54, v146, v60
	s_and_b64 vcc, s[8:9], vcc
	v_max3_f32 v54, v54, v61, v58
	v_cndmask_b32_e32 v56, v176, v65, vcc
	v_max3_f32 v55, v54, v59, v56
	v_add_u32_e32 v54, 0xffffffa0, v143
	v_subrev_u32_e32 v57, 37, v141
; template <int DQK, bool WIN>
; DI void attn_item(const u16* __restrict__ Qb, int ldq, const u16* __restrict__ Kb, int ldk, const u16* __restrict__ Vtb, int qb,
;                   float qscale, float sink2, const u16* __restrict__ zb, int ldz, u16* __restrict__ ob, int ldo, u16* lds) {
;     ...
;           if (MASK) {
;             int kg = k0 + kb * 32 + (i & 3) + 8 * (i >> 2) + 4 * hh;
;             bool ok = kg <= qrow;
;             if (WIN) ok = ok && (qrow - kg < 128);
;             v = ok ? v : -INFINITY;
;             st[kb][i] = v;
;           }
;           mx = fmaxf(mx, v);
;         }
;       mx = fmaxf(mx, __shfl_xor(mx, 32));
;       const float mn = fmaxf(m, mx);
;       if (__any(mn != m)) {
;         const float alpha = __builtin_amdgcn_exp2f((m - mn) * qscale);
;         lsum *= alpha;
; #pragma unroll
;         for (int i = 0; i < 16; ++i) { o[0][i] *= alpha; o[1][i] *= alpha; }
;       }
	v_cmp_gt_i32_e32 vcc, s93, v57
	v_cmp_le_i32_e64 s[8:9], v54, v114
	s_and_b64 vcc, s[8:9], vcc
	v_cndmask_b32_e32 v57, v176, v34, vcc
	v_add_u32_e32 v34, 0xffffffa1, v143
	v_subrev_u32_e32 v54, 38, v141
	v_cmp_gt_i32_e32 vcc, s93, v54
	v_cmp_le_i32_e64 s[8:9], v34, v114
	s_and_b64 vcc, s[8:9], vcc
	v_cndmask_b32_e32 v54, v176, v35, vcc
	v_max3_f32 v34, v55, v57, v54
	v_add_u32_e32 v35, 0xffffffa2, v143
	v_subrev_u32_e32 v55, 39, v141
	v_cmp_gt_i32_e32 vcc, s93, v55
	v_cmp_le_i32_e64 s[8:9], v35, v114
	s_and_b64 vcc, s[8:9], vcc
	v_cndmask_b32_e32 v55, v176, v36, vcc
	v_add_u32_e32 v35, 0xffffffa3, v143
	v_subrev_u32_e32 v36, 40, v141
	v_cmp_gt_i32_e32 vcc, s93, v36
	v_cmp_le_i32_e64 s[8:9], v35, v114
	s_and_b64 vcc, s[8:9], vcc
	v_cndmask_b32_e32 v36, v176, v37, vcc
	v_add_u32_e32 v35, 0xffffffa8, v143
	v_subrev_u32_e32 v37, 45, v141
	v_cmp_gt_i32_e32 vcc, s93, v37
	v_cmp_le_i32_e64 s[8:9], v35, v114
	s_and_b64 vcc, s[8:9], vcc
	v_cndmask_b32_e32 v37, v176, v38, vcc
	v_add_u32_e32 v35, 0xffffffa9, v143
	v_subrev_u32_e32 v38, 46, v141
	v_cmp_gt_i32_e32 vcc, s93, v38
	v_cmp_le_i32_e64 s[8:9], v35, v114
	s_and_b64 vcc, s[8:9], vcc
	v_cndmask_b32_e32 v35, v176, v39, vcc
	v_add_u32_e32 v38, 0xffffffaa, v143
	v_subrev_u32_e32 v39, 47, v141
	v_cmp_gt_i32_e32 vcc, s93, v39
	v_cmp_le_i32_e64 s[8:9], v38, v114
	s_and_b64 vcc, s[8:9], vcc
	v_cndmask_b32_e32 v38, v176, v40, vcc
	v_add_u32_e32 v39, 0xffffffab, v143
	v_subrev_u32_e32 v40, 48, v141
	v_cmp_gt_i32_e32 vcc, s93, v40
	v_cmp_le_i32_e64 s[8:9], v39, v114
	s_and_b64 vcc, s[8:9], vcc
	v_cndmask_b32_e32 v39, v176, v41, vcc
	v_add_u32_e32 v40, 0xffffffb0, v143
	v_subrev_u32_e32 v41, 53, v141
	v_cmp_gt_i32_e32 vcc, s93, v41
	v_cmp_le_i32_e64 s[8:9], v40, v114
	s_and_b64 vcc, s[8:9], vcc
	v_cndmask_b32_e32 v40, v176, v42, vcc
	v_add_u32_e32 v41, 0xffffffb1, v143
	v_subrev_u32_e32 v42, 54, v141
	v_cmp_gt_i32_e32 vcc, s93, v42
	v_cmp_le_i32_e64 s[8:9], v41, v114
	s_and_b64 vcc, s[8:9], vcc
	v_cndmask_b32_e32 v41, v176, v43, vcc
	v_add_u32_e32 v42, 0xffffffb2, v143
	v_subrev_u32_e32 v43, 55, v141
	v_cmp_gt_i32_e32 vcc, s93, v43
	v_cmp_le_i32_e64 s[8:9], v42, v114
	s_and_b64 vcc, s[8:9], vcc
	v_cndmask_b32_e32 v42, v176, v44, vcc
	v_add_u32_e32 v43, 0xffffffb3, v143
	v_subrev_u32_e32 v44, 56, v141
	v_cmp_gt_i32_e32 vcc, s93, v44
	v_cmp_le_i32_e64 s[8:9], v43, v114
	s_and_b64 vcc, s[8:9], vcc
	v_cndmask_b32_e32 v43, v176, v45, vcc
	v_add_u32_e32 v44, 0xffffffb8, v143
	v_subrev_u32_e32 v45, 61, v141
	v_cmp_gt_i32_e32 vcc, s93, v45
	v_cmp_le_i32_e64 s[8:9], v44, v114
	s_and_b64 vcc, s[8:9], vcc
	v_cndmask_b32_e32 v44, v176, v46, vcc
	v_add_u32_e32 v45, 0xffffffb9, v143
	v_subrev_u32_e32 v46, 62, v141
	v_cmp_gt_i32_e32 vcc, s93, v46
	v_cmp_le_i32_e64 s[8:9], v45, v114
	s_and_b64 vcc, s[8:9], vcc
	v_cndmask_b32_e32 v45, v176, v47, vcc
	v_add_u32_e32 v46, 0xffffffba, v143
	v_subrev_u32_e32 v47, 63, v141
	v_cmp_gt_i32_e32 vcc, s93, v47
	v_cmp_le_i32_e64 s[8:9], v46, v114
	s_and_b64 vcc, s[8:9], vcc
	v_cndmask_b32_e32 v46, v176, v48, vcc
	v_add_u32_e32 v47, 0xffffffbb, v143
	v_subrev_u32_e32 v48, 64, v141
	v_max3_f32 v34, v34, v55, v36
	v_cmp_gt_i32_e32 vcc, s93, v48
	v_cmp_le_i32_e64 s[8:9], v47, v114
	v_max3_f32 v34, v34, v37, v35
	s_and_b64 vcc, s[8:9], vcc
	v_max3_f32 v34, v34, v38, v39
	v_cndmask_b32_e32 v47, v176, v49, vcc
	v_and_b32_e32 v49, 64, v172
	v_max3_f32 v34, v34, v40, v41
	v_xor_b32_e32 v48, 32, v172
	v_add_u32_e32 v49, 64, v49
	v_max3_f32 v34, v34, v42, v43
	v_cmp_lt_i32_e32 vcc, v48, v49
	v_max3_f32 v34, v34, v44, v45
	v_max3_f32 v34, v34, v46, v47
	v_cndmask_b32_e32 v48, v172, v48, vcc
	v_lshlrev_b32_e32 v48, 2, v48
	v_mov_b32_e32 v48, v34
	s_nop 1
	v_permlane32_swap_b32 v48, v34
	s_waitcnt lgkmcnt(0)
	v_max3_f32 v34, v144, v34, v48
	v_cmp_neq_f32_e32 vcc, v34, v144
	s_cbranch_vccz .LBB0_326
	v_sub_f32_e32 v48, v144, v34
	v_mul_f32_e32 v48, 0x3e38aa3b, v48
	v_exp_f32_e32 v48, v48
	s_nop 0
	v_mul_f32_e32 v116, v116, v48
	v_pk_mul_f32 v[32:33], v[32:33], v[48:49] op_sel_hi:[1,0]
	v_pk_mul_f32 v[30:31], v[30:31], v[48:49] op_sel_hi:[1,0]
	v_pk_mul_f32 v[28:29], v[28:29], v[48:49] op_sel_hi:[1,0]
	v_pk_mul_f32 v[26:27], v[26:27], v[48:49] op_sel_hi:[1,0]
	v_pk_mul_f32 v[24:25], v[24:25], v[48:49] op_sel_hi:[1,0]
	v_pk_mul_f32 v[22:23], v[22:23], v[48:49] op_sel_hi:[1,0]
	v_pk_mul_f32 v[20:21], v[20:21], v[48:49] op_sel_hi:[1,0]
	v_pk_mul_f32 v[18:19], v[18:19], v[48:49] op_sel_hi:[1,0]
	v_pk_mul_f32 v[16:17], v[16:17], v[48:49] op_sel_hi:[1,0]
	v_pk_mul_f32 v[14:15], v[14:15], v[48:49] op_sel_hi:[1,0]
	v_pk_mul_f32 v[12:13], v[12:13], v[48:49] op_sel_hi:[1,0]
	v_pk_mul_f32 v[10:11], v[10:11], v[48:49] op_sel_hi:[1,0]
	v_pk_mul_f32 v[8:9], v[8:9], v[48:49] op_sel_hi:[1,0]
	v_pk_mul_f32 v[6:7], v[6:7], v[48:49] op_sel_hi:[1,0]
	v_pk_mul_f32 v[4:5], v[4:5], v[48:49] op_sel_hi:[1,0]
	v_pk_mul_f32 v[2:3], v[2:3], v[48:49] op_sel_hi:[1,0]
